# baseline (speedup 1.0000x reference)
_Z11mega_kernel1P:
	s_bitcmp0_b32 s2, 3
	s_cbranch_scc1 .LBB0_prio_b0
	s_cmpk_lt_u32 s2, 0x100
	s_cbranch_scc1 .LBB0_prio_p1
	s_setprio 3
	s_branch .LBB0_prio_done
.LBB0_prio_p1:
	s_setprio 1
	s_branch .LBB0_prio_done
.LBB0_prio_b0:
	s_cmpk_lt_u32 s2, 0x100
	s_cbranch_scc1 .LBB0_prio_done
	s_setprio 2
